# panel barrier between mem-q and mem-attention replaced by a workgroup-local barrier (each member now reads only its own q columns)
# baseline (speedup 1.0000x reference)
.LBB0_1131:
	v_readlane_b32 s0, v253, 27
	v_readlane_b32 s1, v253, 28
	s_and_b64 vcc, exec, s[0:1]
	s_cbranch_vccz .LBB0_1137
	s_xor_b64 s[2:3], s[84:85], -1
	s_mov_b64 s[0:1], -1
	s_and_b64 vcc, exec, s[2:3]
	s_cbranch_vccz .LBB0_1161
	s_waitcnt vmcnt(0)
	v_readlane_b32 s0, v252, 36
	s_add_i32 s26, s0, 1
	s_waitcnt vmcnt(0) lgkmcnt(0)
	s_add_i32 s2, s18, -1
	s_mul_hi_i32 s3, s2, 0x38e38e39
	s_lshr_b32 s4, s3, 31
	s_ashr_i32 s3, s3, 1
	s_add_i32 s3, s3, s4
	s_mul_i32 s3, s3, 9
	s_sub_i32 s2, s2, s3
	s_cmp_lg_u32 s2, 4
	s_cbranch_scc1 .Lpb_full
	s_mov_b32 s26, s0
	s_barrier
	buffer_inv sc1
	s_waitcnt vmcnt(0)
	s_mov_b64 s[0:1], 0
	s_branch .LBB0_1161
.Lpb_full:
	s_barrier
	s_mov_b64 s[0:1], exec
	v_readlane_b32 s2, v251, 5
	v_readlane_b32 s3, v251, 6
	s_and_b64 s[2:3], s[0:1], s[2:3]
	s_mov_b64 exec, s[2:3]
	s_cbranch_execz .LBB0_1160
	s_add_i32 s2, s18, -1
	s_mul_hi_i32 s3, s2, 0x38e38e39
	s_lshr_b32 s4, s3, 31
	s_ashr_i32 s3, s3, 1
	s_add_i32 s3, s3, s4
	s_mul_i32 s3, s3, 9
	s_sub_i32 s2, s2, s3
	s_cmp_lg_u32 s2, 7
	v_readlane_b32 s4, v252, 43
	s_cselect_b64 s[2:3], -1, 0
	v_readlane_b32 s5, v252, 44
	s_and_b64 s[2:3], s[4:5], s[2:3]
	s_and_b64 vcc, exec, s[2:3]
	s_cbranch_vccnz .LBB0_1136
	buffer_wbl2 sc1
	s_waitcnt vmcnt(0)
